# GEMM mainloops: LDS-DMA interleaved among ds_reads (s_nop wait states removed); accumulator zeroing with v_mov_b64
# speedup vs baseline: 1.0020x; 1.0020x over previous
; #define PG8_STAGE(bufoff, gbase, voff) do { _Pragma("unroll") for (int _i = 0; _i < 2; ++_i) \
;         __builtin_amdgcn_global_load_lds((const unsigned*)((const char*)(gbase) + (voff)[_i]), (LAS unsigned*)(lds + (bufoff) + ldsw + _i * 8192), 16, 0, 0); } while (0)
; #define PG8_LDA(dst, b, h) do { _Pragma("unroll") for (int m = 0; m < 4; ++m) _Pragma("unroll") for (int k = 0; k < 2; ++k) dst[m][k] = *(const LAS bf16x8*)(lds + PG8_SA(b, h) + aoff + m * 2048 + k * 1024); } while (0)
; #define PG8_LDB(dst, b, h) do { _Pragma("unroll") for (int n = 0; n < 2; ++n) _Pragma("unroll") for (int k = 0; k < 2; ++k) dst[n][k] = *(const LAS bf16x8*)(lds + PG8_SB(b, h) + boff + n * 2048 + k * 1024); } while (0)
; #define PG8_MMA(ai, bj, At, Bt) do { __builtin_amdgcn_s_setprio(1); _Pragma("unroll") for (int m = 0; m < 4; ++m) _Pragma("unroll") for (int n = 0; n < 2; ++n) _Pragma("unroll") for (int k = 0; k < 2; ++k) \
;         acc[ai][bj][m][n] = __builtin_amdgcn_mfma_f32_16x16x32_bf16(Bt[n][k], At[m][k], acc[ai][bj][m][n], 0, 0, 0); __builtin_amdgcn_s_setprio(0); } while (0)
; #define PG8_WAIT_V(n) asm volatile("s_waitcnt vmcnt(" #n ")" ::: "memory")
; #define PG8_WAIT_L(n) asm volatile("s_waitcnt lgkmcnt(" #n ")" ::: "memory")
; #define PG8_BAR __builtin_amdgcn_s_barrier()
; #define PG8_SCHED __builtin_amdgcn_sched_barrier(0)
; template <class Epi>
; __device__ __forceinline__ void gemm_phase(LAS unsigned char* lds, const Gemm g, const StaticOrder& S, const Epi& E) {
;     ...
;         for (int t = 0; t < nt; t += 2) {
;             const bool last = (t == nt - 2);
;             const char* a1 = cA + (size_t)(t + 1) * kstep;
;             const char* a2 = last ? nA : cA + (size_t)(t + 2) * kstep; const char* b2 = last ? nB : cB + (size_t)(t + 2) * kstep;
;             const char* a3 = a2 + kstep; const char* b3 = b2 + kstep;
;             PG8_LDB(B0, 0, 0); PG8_LDB(B1, 0, 1); PG8_SCHED; PG8_LDA(At, 0, 0); PG8_STAGE(PG8_SA(1, 1), a1 + hstepA, voffA);
;             PG8_WAIT_V(8); PG8_WAIT_L(0); PG8_BAR; PG8_MMA(0, 0, At, B0); PG8_MMA(0, 1, At, B1); PG8_BAR; PG8_SCHED;
;             PG8_LDA(At, 0, 1); PG8_STAGE(PG8_SB(0, 0), b2, voffB); PG8_STAGE(PG8_SB(0, 1), b2 + hstepB, voffB); PG8_STAGE(PG8_SA(0, 0), a2, voffA);
;             PG8_WAIT_V(8); PG8_WAIT_L(0); PG8_BAR; PG8_MMA(1, 0, At, B0); PG8_MMA(1, 1, At, B1); PG8_BAR; PG8_SCHED;
.LBB0_233:
	s_add_i32 s83, s26, 2
	s_add_u32 vcc_lo, s12, 0x80
	s_addc_u32 s27, s13, 0
	s_add_i32 s52, 0, 0x10000
	s_cmp_eq_u32 s61, s26
	s_cselect_b32 s27, s3, s27
	s_cselect_b32 s26, s2, vcc_lo
	v_add_u32_e32 v155, s52, v145
	s_cselect_b32 vcc_hi, s25, s82
	s_cselect_b32 vcc_lo, s24, s57
	s_add_i32 s53, 0, 0x14000
	ds_read_b128 v[140:143], v155
	ds_read_b128 v[156:159], v155 offset:1024
	ds_read_b128 v[166:169], v155 offset:2048
	ds_read_b128 v[170:173], v155 offset:3072
	v_add_u32_e32 v155, s53, v145
	ds_read_b128 v[174:177], v155
	ds_read_b128 v[178:181], v155 offset:1024
	ds_read_b128 v[194:197], v155 offset:2048
	ds_read_b128 v[198:201], v155 offset:3072
	s_add_i32 m0, s30, 0xc000
	ds_read_b128 v[202:205], v154
	global_load_lds_dwordx4 v136, s[12:13]
	s_add_i32 m0, s30, 0xe000
	ds_read_b128 v[206:209], v154 offset:1024
	global_load_lds_dwordx4 v138, s[12:13]
	ds_read_b128 v[210:213], v154 offset:2048
	ds_read_b128 v[214:217], v154 offset:3072
	ds_read_b128 v[218:221], v154 offset:4096
	ds_read_b128 v[222:225], v154 offset:5120
	ds_read_b128 v[226:229], v154 offset:6144
	ds_read_b128 v[234:237], v154 offset:7168
	s_waitcnt vmcnt(8)
	s_waitcnt lgkmcnt(0)
	s_setprio 1
	s_barrier
	v_mfma_f32_16x16x32_bf16 v[126:129], v[140:143], v[202:205], v[126:129]
	v_mfma_f32_16x16x32_bf16 v[122:125], v[166:169], v[202:205], v[122:125]
	v_mfma_f32_16x16x32_bf16 v[110:113], v[140:143], v[210:213], v[110:113]
	v_mfma_f32_16x16x32_bf16 v[106:109], v[166:169], v[210:213], v[106:109]
	v_mfma_f32_16x16x32_bf16 v[94:97], v[140:143], v[218:221], v[94:97]
	v_mfma_f32_16x16x32_bf16 v[90:93], v[166:169], v[218:221], v[90:93]
	v_mfma_f32_16x16x32_bf16 v[78:81], v[140:143], v[226:229], v[78:81]
	v_mfma_f32_16x16x32_bf16 v[74:77], v[166:169], v[226:229], v[74:77]
	v_mfma_f32_16x16x32_bf16 v[126:129], v[156:159], v[206:209], v[126:129]
	v_mfma_f32_16x16x32_bf16 v[122:125], v[170:173], v[206:209], v[122:125]
	v_mfma_f32_16x16x32_bf16 v[110:113], v[156:159], v[214:217], v[110:113]
	v_mfma_f32_16x16x32_bf16 v[106:109], v[170:173], v[214:217], v[106:109]
	v_mfma_f32_16x16x32_bf16 v[94:97], v[156:159], v[222:225], v[94:97]
	v_mfma_f32_16x16x32_bf16 v[90:93], v[170:173], v[222:225], v[90:93]
	v_mfma_f32_16x16x32_bf16 v[78:81], v[156:159], v[234:237], v[78:81]
	v_mfma_f32_16x16x32_bf16 v[74:77], v[170:173], v[234:237], v[74:77]
	v_mfma_f32_16x16x32_bf16 v[118:121], v[174:177], v[202:205], v[118:121]
	v_mfma_f32_16x16x32_bf16 v[114:117], v[194:197], v[202:205], v[114:117]
	v_mfma_f32_16x16x32_bf16 v[102:105], v[174:177], v[210:213], v[102:105]
	v_mfma_f32_16x16x32_bf16 v[98:101], v[194:197], v[210:213], v[98:101]
	v_mfma_f32_16x16x32_bf16 v[86:89], v[174:177], v[218:221], v[86:89]
	v_mfma_f32_16x16x32_bf16 v[82:85], v[194:197], v[218:221], v[82:85]
	v_mfma_f32_16x16x32_bf16 v[70:73], v[174:177], v[226:229], v[70:73]
	v_mfma_f32_16x16x32_bf16 v[66:69], v[194:197], v[226:229], v[66:69]
	v_mfma_f32_16x16x32_bf16 v[118:121], v[178:181], v[206:209], v[118:121]
	v_mfma_f32_16x16x32_bf16 v[114:117], v[198:201], v[206:209], v[114:117]
	v_mfma_f32_16x16x32_bf16 v[102:105], v[178:181], v[214:217], v[102:105]
	v_mfma_f32_16x16x32_bf16 v[98:101], v[198:201], v[214:217], v[98:101]
	v_mfma_f32_16x16x32_bf16 v[86:89], v[178:181], v[222:225], v[86:89]
	v_mfma_f32_16x16x32_bf16 v[82:85], v[198:201], v[222:225], v[82:85]
	v_mfma_f32_16x16x32_bf16 v[70:73], v[178:181], v[234:237], v[70:73]
	v_mfma_f32_16x16x32_bf16 v[66:69], v[198:201], v[234:237], v[66:69]
	s_barrier
	s_setprio 0
	s_add_i32 s52, s52, s41
	s_mov_b32 m0, s52
	ds_read_b128 v[202:205], v154 offset:16384
	global_load_lds_dwordx4 v0, vcc
	s_add_i32 m0, s52, 0x2000
	s_add_i32 s52, s53, s41
	ds_read_b128 v[206:209], v154 offset:17408
	global_load_lds_dwordx4 v134, vcc
	s_add_u32 vcc_lo, vcc_lo, s23
	s_addc_u32 vcc_hi, vcc_hi, 0
	s_mov_b32 m0, s52
	ds_read_b128 v[210:213], v154 offset:18432
	global_load_lds_dwordx4 v0, vcc
	s_add_i32 m0, s52, 0x2000
	ds_read_b128 v[214:217], v154 offset:19456
	global_load_lds_dwordx4 v134, vcc
	s_mov_b32 m0, s30
	ds_read_b128 v[218:221], v154 offset:20480
	global_load_lds_dwordx4 v130, s[26:27]
	s_mov_b32 m0, s31
	ds_read_b128 v[222:225], v154 offset:21504
	global_load_lds_dwordx4 v132, s[26:27]
	ds_read_b128 v[226:229], v154 offset:22528
	ds_read_b128 v[234:237], v154 offset:23552
	s_waitcnt vmcnt(8)
	s_waitcnt lgkmcnt(0)
	s_setprio 1
	s_barrier
	v_mfma_f32_16x16x32_bf16 v[62:65], v[140:143], v[202:205], v[62:65]
	v_mfma_f32_16x16x32_bf16 v[58:61], v[166:169], v[202:205], v[58:61]
	v_mfma_f32_16x16x32_bf16 v[46:49], v[140:143], v[210:213], v[46:49]
	v_mfma_f32_16x16x32_bf16 v[42:45], v[166:169], v[210:213], v[42:45]
	v_mfma_f32_16x16x32_bf16 v[30:33], v[140:143], v[218:221], v[30:33]
	v_mfma_f32_16x16x32_bf16 v[26:29], v[166:169], v[218:221], v[26:29]
	v_mfma_f32_16x16x32_bf16 v[14:17], v[140:143], v[226:229], v[14:17]
	v_mfma_f32_16x16x32_bf16 v[10:13], v[166:169], v[226:229], v[10:13]
	v_mfma_f32_16x16x32_bf16 v[62:65], v[156:159], v[206:209], v[62:65]
	v_mfma_f32_16x16x32_bf16 v[58:61], v[170:173], v[206:209], v[58:61]
	v_mfma_f32_16x16x32_bf16 v[46:49], v[156:159], v[214:217], v[46:49]
	v_mfma_f32_16x16x32_bf16 v[42:45], v[170:173], v[214:217], v[42:45]
	v_mfma_f32_16x16x32_bf16 v[30:33], v[156:159], v[222:225], v[30:33]
	v_mfma_f32_16x16x32_bf16 v[26:29], v[170:173], v[222:225], v[26:29]
	v_mfma_f32_16x16x32_bf16 v[14:17], v[156:159], v[234:237], v[14:17]
	v_mfma_f32_16x16x32_bf16 v[10:13], v[170:173], v[234:237], v[10:13]
	v_mfma_f32_16x16x32_bf16 v[54:57], v[174:177], v[202:205], v[54:57]
	v_mfma_f32_16x16x32_bf16 v[50:53], v[194:197], v[202:205], v[50:53]
	v_mfma_f32_16x16x32_bf16 v[38:41], v[174:177], v[210:213], v[38:41]
	v_mfma_f32_16x16x32_bf16 v[34:37], v[194:197], v[210:213], v[34:37]
	v_mfma_f32_16x16x32_bf16 v[22:25], v[174:177], v[218:221], v[22:25]
	v_mfma_f32_16x16x32_bf16 v[18:21], v[194:197], v[218:221], v[18:21]
	v_mfma_f32_16x16x32_bf16 v[6:9], v[174:177], v[226:229], v[6:9]
	v_mfma_f32_16x16x32_bf16 v[2:5], v[194:197], v[226:229], v[2:5]
	v_mfma_f32_16x16x32_bf16 v[54:57], v[178:181], v[206:209], v[54:57]
	v_mfma_f32_16x16x32_bf16 v[50:53], v[198:201], v[206:209], v[50:53]
	v_mfma_f32_16x16x32_bf16 v[38:41], v[178:181], v[214:217], v[38:41]
	v_mfma_f32_16x16x32_bf16 v[34:37], v[198:201], v[214:217], v[34:37]
	v_mfma_f32_16x16x32_bf16 v[22:25], v[178:181], v[222:225], v[22:25]
	v_mfma_f32_16x16x32_bf16 v[18:21], v[198:201], v[222:225], v[18:21]
	v_mfma_f32_16x16x32_bf16 v[6:9], v[178:181], v[234:237], v[6:9]
	v_mfma_f32_16x16x32_bf16 v[2:5], v[198:201], v[234:237], v[2:5]
	s_barrier
; #define PG8_STAGE(bufoff, gbase, voff) do { _Pragma("unroll") for (int _i = 0; _i < 2; ++_i) \
;         __builtin_amdgcn_global_load_lds((const unsigned*)((const char*)(gbase) + (voff)[_i]), (LAS unsigned*)(lds + (bufoff) + ldsw + _i * 8192), 16, 0, 0); } while (0)
; #define PG8_LDA(dst, b, h) do { _Pragma("unroll") for (int m = 0; m < 4; ++m) _Pragma("unroll") for (int k = 0; k < 2; ++k) dst[m][k] = *(const LAS bf16x8*)(lds + PG8_SA(b, h) + aoff + m * 2048 + k * 1024); } while (0)
; #define PG8_LDB(dst, b, h) do { _Pragma("unroll") for (int n = 0; n < 2; ++n) _Pragma("unroll") for (int k = 0; k < 2; ++k) dst[n][k] = *(const LAS bf16x8*)(lds + PG8_SB(b, h) + boff + n * 2048 + k * 1024); } while (0)
; #define PG8_MMA(ai, bj, At, Bt) do { __builtin_amdgcn_s_setprio(1); _Pragma("unroll") for (int m = 0; m < 4; ++m) _Pragma("unroll") for (int n = 0; n < 2; ++n) _Pragma("unroll") for (int k = 0; k < 2; ++k) \
;         acc[ai][bj][m][n] = __builtin_amdgcn_mfma_f32_16x16x32_bf16(Bt[n][k], At[m][k], acc[ai][bj][m][n], 0, 0, 0); __builtin_amdgcn_s_setprio(0); } while (0)
; #define PG8_WAIT_V(n) asm volatile("s_waitcnt vmcnt(" #n ")" ::: "memory")
; #define PG8_WAIT_L(n) asm volatile("s_waitcnt lgkmcnt(" #n ")" ::: "memory")
; #define PG8_BAR __builtin_amdgcn_s_barrier()
; #define PG8_SCHED __builtin_amdgcn_sched_barrier(0)
; template <class Epi>
; __device__ __forceinline__ void gemm_phase(LAS unsigned char* lds, const Gemm g, const StaticOrder& S, const Epi& E) {
;     ...
;             PG8_LDB(B0, 1, 0); PG8_LDB(B1, 1, 1); PG8_SCHED; PG8_LDA(At, 1, 0); PG8_STAGE(PG8_SA(0, 1), a2 + hstepA, voffA);
;             PG8_WAIT_V(8); PG8_WAIT_L(0); PG8_BAR; PG8_MMA(0, 0, At, B0); PG8_MMA(0, 1, At, B1); PG8_BAR; PG8_SCHED;
;             PG8_LDA(At, 1, 1); PG8_STAGE(PG8_SB(1, 0), b3, voffB); PG8_STAGE(PG8_SB(1, 1), b3 + hstepB, voffB); PG8_STAGE(PG8_SA(1, 0), a3, voffA);
;             PG8_WAIT_V(8); PG8_WAIT_L(0); PG8_BAR; PG8_MMA(1, 0, At, B0); PG8_MMA(1, 1, At, B1); PG8_BAR; PG8_SCHED;
;         }
;         if (wr == 0) PG8_BAR;
	s_setprio 0
	s_add_i32 s52, 0, 0x18000
	v_add_u32_e32 v155, s52, v145
	s_add_i32 s53, 0, 0x1c000
	ds_read_b128 v[140:143], v155
	ds_read_b128 v[156:159], v155 offset:1024
	ds_read_b128 v[166:169], v155 offset:2048
	ds_read_b128 v[170:173], v155 offset:3072
	v_add_u32_e32 v155, s53, v145
	ds_read_b128 v[174:177], v155
	ds_read_b128 v[178:181], v155 offset:1024
	ds_read_b128 v[194:197], v155 offset:2048
	ds_read_b128 v[198:201], v155 offset:3072
	s_add_u32 s26, s26, s78
	s_addc_u32 s27, s27, 0
	s_mov_b32 m0, s64
	ds_read_b128 v[202:205], v154 offset:32768
	global_load_lds_dwordx4 v130, s[26:27]
	s_mov_b32 m0, s85
	ds_read_b128 v[206:209], v154 offset:33792
	global_load_lds_dwordx4 v132, s[26:27]
	ds_read_b128 v[210:213], v154 offset:34816
	ds_read_b128 v[214:217], v154 offset:35840
	ds_read_b128 v[218:221], v154 offset:36864
	ds_read_b128 v[222:225], v154 offset:37888
	ds_read_b128 v[226:229], v154 offset:38912
	ds_read_b128 v[234:237], v154 offset:39936
	s_waitcnt vmcnt(8)
	s_waitcnt lgkmcnt(0)
	s_setprio 1
	s_barrier
	v_mfma_f32_16x16x32_bf16 v[126:129], v[140:143], v[202:205], v[126:129]
	v_mfma_f32_16x16x32_bf16 v[122:125], v[166:169], v[202:205], v[122:125]
	v_mfma_f32_16x16x32_bf16 v[110:113], v[140:143], v[210:213], v[110:113]
	v_mfma_f32_16x16x32_bf16 v[106:109], v[166:169], v[210:213], v[106:109]
	v_mfma_f32_16x16x32_bf16 v[94:97], v[140:143], v[218:221], v[94:97]
	v_mfma_f32_16x16x32_bf16 v[90:93], v[166:169], v[218:221], v[90:93]
	v_mfma_f32_16x16x32_bf16 v[78:81], v[140:143], v[226:229], v[78:81]
	v_mfma_f32_16x16x32_bf16 v[74:77], v[166:169], v[226:229], v[74:77]
	v_mfma_f32_16x16x32_bf16 v[126:129], v[156:159], v[206:209], v[126:129]
	v_mfma_f32_16x16x32_bf16 v[122:125], v[170:173], v[206:209], v[122:125]
	v_mfma_f32_16x16x32_bf16 v[110:113], v[156:159], v[214:217], v[110:113]
	v_mfma_f32_16x16x32_bf16 v[106:109], v[170:173], v[214:217], v[106:109]
	v_mfma_f32_16x16x32_bf16 v[94:97], v[156:159], v[222:225], v[94:97]
	v_mfma_f32_16x16x32_bf16 v[90:93], v[170:173], v[222:225], v[90:93]
	v_mfma_f32_16x16x32_bf16 v[78:81], v[156:159], v[234:237], v[78:81]
	v_mfma_f32_16x16x32_bf16 v[74:77], v[170:173], v[234:237], v[74:77]
	v_mfma_f32_16x16x32_bf16 v[118:121], v[174:177], v[202:205], v[118:121]
	v_mfma_f32_16x16x32_bf16 v[114:117], v[194:197], v[202:205], v[114:117]
	v_mfma_f32_16x16x32_bf16 v[102:105], v[174:177], v[210:213], v[102:105]
	v_mfma_f32_16x16x32_bf16 v[98:101], v[194:197], v[210:213], v[98:101]
	v_mfma_f32_16x16x32_bf16 v[86:89], v[174:177], v[218:221], v[86:89]
	v_mfma_f32_16x16x32_bf16 v[82:85], v[194:197], v[218:221], v[82:85]
	v_mfma_f32_16x16x32_bf16 v[70:73], v[174:177], v[226:229], v[70:73]
	v_mfma_f32_16x16x32_bf16 v[66:69], v[194:197], v[226:229], v[66:69]
	v_mfma_f32_16x16x32_bf16 v[118:121], v[178:181], v[206:209], v[118:121]
	v_mfma_f32_16x16x32_bf16 v[114:117], v[198:201], v[206:209], v[114:117]
	v_mfma_f32_16x16x32_bf16 v[102:105], v[178:181], v[214:217], v[102:105]
	v_mfma_f32_16x16x32_bf16 v[98:101], v[198:201], v[214:217], v[98:101]
	v_mfma_f32_16x16x32_bf16 v[86:89], v[178:181], v[222:225], v[86:89]
	v_mfma_f32_16x16x32_bf16 v[82:85], v[198:201], v[222:225], v[82:85]
	v_mfma_f32_16x16x32_bf16 v[70:73], v[178:181], v[234:237], v[70:73]
	v_mfma_f32_16x16x32_bf16 v[66:69], v[198:201], v[234:237], v[66:69]
	s_barrier
	s_setprio 0
	s_add_i32 s32, s52, s41
	s_sub_u32 vcc_lo, vcc_lo, s23
	s_subb_u32 vcc_hi, vcc_hi, 0
	s_add_u32 vcc_lo, vcc_lo, 0x80
	s_addc_u32 vcc_hi, vcc_hi, 0
	s_mov_b32 m0, s32
	ds_read_b128 v[202:205], v154 offset:49152
	global_load_lds_dwordx4 v0, vcc
	s_add_i32 m0, s32, 0x2000
	s_add_i32 s32, s53, s41
	ds_read_b128 v[206:209], v154 offset:50176
	global_load_lds_dwordx4 v134, vcc
	s_add_u32 vcc_lo, vcc_lo, s23
	s_addc_u32 vcc_hi, vcc_hi, 0
	s_mov_b32 m0, s32
	ds_read_b128 v[210:213], v154 offset:51200
	global_load_lds_dwordx4 v0, vcc
	s_add_i32 m0, s32, 0x2000
	s_sub_u32 s26, s26, s78
	s_subb_u32 s27, s27, 0
	ds_read_b128 v[214:217], v154 offset:52224
	global_load_lds_dwordx4 v134, vcc
	s_add_u32 s26, s26, 0x80
	s_addc_u32 s27, s27, 0
	s_mov_b32 m0, s92
	ds_read_b128 v[218:221], v154 offset:53248
	global_load_lds_dwordx4 v130, s[26:27]
	s_mov_b32 m0, s93
	ds_read_b128 v[222:225], v154 offset:54272
	global_load_lds_dwordx4 v132, s[26:27]
	ds_read_b128 v[226:229], v154 offset:55296
	ds_read_b128 v[234:237], v154 offset:56320
	s_waitcnt vmcnt(8)
	s_waitcnt lgkmcnt(0)
	s_setprio 1
	s_barrier
	v_mfma_f32_16x16x32_bf16 v[62:65], v[140:143], v[202:205], v[62:65]
	v_mfma_f32_16x16x32_bf16 v[58:61], v[166:169], v[202:205], v[58:61]
	v_mfma_f32_16x16x32_bf16 v[46:49], v[140:143], v[210:213], v[46:49]
	v_mfma_f32_16x16x32_bf16 v[42:45], v[166:169], v[210:213], v[42:45]
	v_mfma_f32_16x16x32_bf16 v[30:33], v[140:143], v[218:221], v[30:33]
	v_mfma_f32_16x16x32_bf16 v[26:29], v[166:169], v[218:221], v[26:29]
	v_mfma_f32_16x16x32_bf16 v[14:17], v[140:143], v[226:229], v[14:17]
	v_mfma_f32_16x16x32_bf16 v[10:13], v[166:169], v[226:229], v[10:13]
	v_mfma_f32_16x16x32_bf16 v[62:65], v[156:159], v[206:209], v[62:65]
	v_mfma_f32_16x16x32_bf16 v[58:61], v[170:173], v[206:209], v[58:61]
	v_mfma_f32_16x16x32_bf16 v[46:49], v[156:159], v[214:217], v[46:49]
	v_mfma_f32_16x16x32_bf16 v[42:45], v[170:173], v[214:217], v[42:45]
	v_mfma_f32_16x16x32_bf16 v[30:33], v[156:159], v[222:225], v[30:33]
	v_mfma_f32_16x16x32_bf16 v[26:29], v[170:173], v[222:225], v[26:29]
	v_mfma_f32_16x16x32_bf16 v[14:17], v[156:159], v[234:237], v[14:17]
	v_mfma_f32_16x16x32_bf16 v[10:13], v[170:173], v[234:237], v[10:13]
	v_mfma_f32_16x16x32_bf16 v[54:57], v[174:177], v[202:205], v[54:57]
	v_mfma_f32_16x16x32_bf16 v[50:53], v[194:197], v[202:205], v[50:53]
	v_mfma_f32_16x16x32_bf16 v[38:41], v[174:177], v[210:213], v[38:41]
	v_mfma_f32_16x16x32_bf16 v[34:37], v[194:197], v[210:213], v[34:37]
	v_mfma_f32_16x16x32_bf16 v[22:25], v[174:177], v[218:221], v[22:25]
	v_mfma_f32_16x16x32_bf16 v[18:21], v[194:197], v[218:221], v[18:21]
	v_mfma_f32_16x16x32_bf16 v[6:9], v[174:177], v[226:229], v[6:9]
	v_mfma_f32_16x16x32_bf16 v[2:5], v[194:197], v[226:229], v[2:5]
	v_mfma_f32_16x16x32_bf16 v[54:57], v[178:181], v[206:209], v[54:57]
	v_mfma_f32_16x16x32_bf16 v[50:53], v[198:201], v[206:209], v[50:53]
	v_mfma_f32_16x16x32_bf16 v[38:41], v[178:181], v[214:217], v[38:41]
	v_mfma_f32_16x16x32_bf16 v[34:37], v[198:201], v[214:217], v[34:37]
	v_mfma_f32_16x16x32_bf16 v[22:25], v[178:181], v[222:225], v[22:25]
	v_mfma_f32_16x16x32_bf16 v[18:21], v[198:201], v[222:225], v[18:21]
	v_mfma_f32_16x16x32_bf16 v[6:9], v[178:181], v[234:237], v[6:9]
	v_mfma_f32_16x16x32_bf16 v[2:5], v[198:201], v[234:237], v[2:5]
	s_barrier
	s_setprio 0
	s_add_u32 s12, s12, 0x100
	s_addc_u32 s13, s13, 0
	s_add_u32 s57, s57, 0x100
	s_addc_u32 s82, s82, 0
	s_cmp_ge_u32 s83, s80
	s_mov_b32 s26, s83
	s_cbranch_scc0 .LBB0_233
	s_and_b64 vcc, exec, s[74:75]
	s_cbranch_vccz .LBB0_236
	s_barrier

; #define PG8_STAGE(bufoff, gbase, voff) do { _Pragma("unroll") for (int _i = 0; _i < 2; ++_i) \
;         __builtin_amdgcn_global_load_lds((const unsigned*)((const char*)(gbase) + (voff)[_i]), (LAS unsigned*)(lds + (bufoff) + ldsw + _i * 8192), 16, 0, 0); } while (0)
; #define PG8_LDA(dst, b, h) do { _Pragma("unroll") for (int m = 0; m < 4; ++m) _Pragma("unroll") for (int k = 0; k < 2; ++k) dst[m][k] = *(const LAS bf16x8*)(lds + PG8_SA(b, h) + aoff + m * 2048 + k * 1024); } while (0)
; #define PG8_LDB(dst, b, h) do { _Pragma("unroll") for (int n = 0; n < 2; ++n) _Pragma("unroll") for (int k = 0; k < 2; ++k) dst[n][k] = *(const LAS bf16x8*)(lds + PG8_SB(b, h) + boff + n * 2048 + k * 1024); } while (0)
; #define PG8_MMA(ai, bj, At, Bt) do { __builtin_amdgcn_s_setprio(1); _Pragma("unroll") for (int m = 0; m < 4; ++m) _Pragma("unroll") for (int n = 0; n < 2; ++n) _Pragma("unroll") for (int k = 0; k < 2; ++k) \
;         acc[ai][bj][m][n] = __builtin_amdgcn_mfma_f32_16x16x32_bf16(Bt[n][k], At[m][k], acc[ai][bj][m][n], 0, 0, 0); __builtin_amdgcn_s_setprio(0); } while (0)
; #define PG8_WAIT_V(n) asm volatile("s_waitcnt vmcnt(" #n ")" ::: "memory")
; #define PG8_WAIT_L(n) asm volatile("s_waitcnt lgkmcnt(" #n ")" ::: "memory")
; #define PG8_BAR __builtin_amdgcn_s_barrier()
; #define PG8_SCHED __builtin_amdgcn_sched_barrier(0)
; template <class Epi>
; __device__ __forceinline__ void gemm_phase(LAS unsigned char* lds, const Gemm g, const StaticOrder& S, const Epi& E) {
;     ...
;         for (int t = 0; t < nt; t += 2) {
;             const bool last = (t == nt - 2);
;             const char* a1 = cA + (size_t)(t + 1) * kstep;
;             const char* a2 = last ? nA : cA + (size_t)(t + 2) * kstep; const char* b2 = last ? nB : cB + (size_t)(t + 2) * kstep;
;             const char* a3 = a2 + kstep; const char* b3 = b2 + kstep;
;             PG8_LDB(B0, 0, 0); PG8_LDB(B1, 0, 1); PG8_SCHED; PG8_LDA(At, 0, 0); PG8_STAGE(PG8_SA(1, 1), a1 + hstepA, voffA);
;             PG8_WAIT_V(8); PG8_WAIT_L(0); PG8_BAR; PG8_MMA(0, 0, At, B0); PG8_MMA(0, 1, At, B1); PG8_BAR; PG8_SCHED;
;             PG8_LDA(At, 0, 1); PG8_STAGE(PG8_SB(0, 0), b2, voffB); PG8_STAGE(PG8_SB(0, 1), b2 + hstepB, voffB); PG8_STAGE(PG8_SA(0, 0), a2, voffA);
;             PG8_WAIT_V(8); PG8_WAIT_L(0); PG8_BAR; PG8_MMA(1, 0, At, B0); PG8_MMA(1, 1, At, B1); PG8_BAR; PG8_SCHED;
.LBB0_295:
	s_add_u32 s26, s24, 0xfff80080
	s_addc_u32 s27, s25, -1
	s_add_i32 s50, 0, 0x10000
	s_cmp_eq_u32 s49, 28
	s_cselect_b32 s35, s13, s27
	s_cselect_b32 s34, s43, s26
	s_cselect_b32 s27, s11, s48
	s_cselect_b32 s26, s46, s47
	s_add_i32 s56, 0, 0x14000
	v_add_u32_e32 v156, s50, v145
	v_add_u32_e32 v160, s56, v145
	ds_read_b128 v[140:143], v156
	ds_read_b128 v[148:151], v156 offset:1024
	ds_read_b128 v[152:155], v156 offset:2048
	ds_read_b128 v[156:159], v156 offset:3072
	ds_read_b128 v[166:169], v160
	ds_read_b128 v[170:173], v160 offset:1024
	ds_read_b128 v[174:177], v160 offset:2048
	ds_read_b128 v[178:181], v160 offset:3072
	s_add_i32 m0, s19, 0xc000
	ds_read_b128 v[194:197], v147
	global_load_lds_dwordx4 v136, s[24:25]
	s_add_i32 m0, s19, 0xe000
	ds_read_b128 v[198:201], v147 offset:1024
	global_load_lds_dwordx4 v138, s[24:25]
	ds_read_b128 v[202:205], v147 offset:2048
	ds_read_b128 v[206:209], v147 offset:3072
	ds_read_b128 v[210:213], v147 offset:4096
	ds_read_b128 v[214:217], v147 offset:5120
	ds_read_b128 v[218:221], v147 offset:6144
	ds_read_b128 v[222:225], v147 offset:7168
	s_waitcnt vmcnt(8)
	s_waitcnt lgkmcnt(0)
	s_setprio 1
	s_barrier
	v_mfma_f32_16x16x32_bf16 v[126:129], v[140:143], v[194:197], v[126:129]
	v_mfma_f32_16x16x32_bf16 v[122:125], v[152:155], v[194:197], v[122:125]
	v_mfma_f32_16x16x32_bf16 v[110:113], v[140:143], v[202:205], v[110:113]
	v_mfma_f32_16x16x32_bf16 v[106:109], v[152:155], v[202:205], v[106:109]
	v_mfma_f32_16x16x32_bf16 v[94:97], v[140:143], v[210:213], v[94:97]
	v_mfma_f32_16x16x32_bf16 v[90:93], v[152:155], v[210:213], v[90:93]
	v_mfma_f32_16x16x32_bf16 v[78:81], v[140:143], v[218:221], v[78:81]
	v_mfma_f32_16x16x32_bf16 v[74:77], v[152:155], v[218:221], v[74:77]
	v_mfma_f32_16x16x32_bf16 v[126:129], v[148:151], v[198:201], v[126:129]
	v_mfma_f32_16x16x32_bf16 v[122:125], v[156:159], v[198:201], v[122:125]
	v_mfma_f32_16x16x32_bf16 v[110:113], v[148:151], v[206:209], v[110:113]
	v_mfma_f32_16x16x32_bf16 v[106:109], v[156:159], v[206:209], v[106:109]
	v_mfma_f32_16x16x32_bf16 v[94:97], v[148:151], v[214:217], v[94:97]
	v_mfma_f32_16x16x32_bf16 v[90:93], v[156:159], v[214:217], v[90:93]
	v_mfma_f32_16x16x32_bf16 v[78:81], v[148:151], v[222:225], v[78:81]
	v_mfma_f32_16x16x32_bf16 v[74:77], v[156:159], v[222:225], v[74:77]
	v_mfma_f32_16x16x32_bf16 v[118:121], v[166:169], v[194:197], v[118:121]
	v_mfma_f32_16x16x32_bf16 v[114:117], v[174:177], v[194:197], v[114:117]
	v_mfma_f32_16x16x32_bf16 v[102:105], v[166:169], v[202:205], v[102:105]
	v_mfma_f32_16x16x32_bf16 v[98:101], v[174:177], v[202:205], v[98:101]
	v_mfma_f32_16x16x32_bf16 v[86:89], v[166:169], v[210:213], v[86:89]
	v_mfma_f32_16x16x32_bf16 v[82:85], v[174:177], v[210:213], v[82:85]
	v_mfma_f32_16x16x32_bf16 v[70:73], v[166:169], v[218:221], v[70:73]
	v_mfma_f32_16x16x32_bf16 v[66:69], v[174:177], v[218:221], v[66:69]
	v_mfma_f32_16x16x32_bf16 v[118:121], v[170:173], v[198:201], v[118:121]
	v_mfma_f32_16x16x32_bf16 v[114:117], v[178:181], v[198:201], v[114:117]
	v_mfma_f32_16x16x32_bf16 v[102:105], v[170:173], v[206:209], v[102:105]
	v_mfma_f32_16x16x32_bf16 v[98:101], v[178:181], v[206:209], v[98:101]
	v_mfma_f32_16x16x32_bf16 v[86:89], v[170:173], v[214:217], v[86:89]
	v_mfma_f32_16x16x32_bf16 v[82:85], v[178:181], v[214:217], v[82:85]
	v_mfma_f32_16x16x32_bf16 v[70:73], v[170:173], v[222:225], v[70:73]
	v_mfma_f32_16x16x32_bf16 v[66:69], v[178:181], v[222:225], v[66:69]
	s_barrier
	s_setprio 0
	s_add_i32 s50, s50, s23
	s_mov_b32 m0, s50
	ds_read_b128 v[194:197], v147 offset:16384
	global_load_lds_dwordx4 v0, s[26:27]
	s_add_i32 m0, s50, 0x2000
	s_add_u32 s50, s26, 0x80000
	s_addc_u32 s51, s27, 0
	s_add_i32 s56, s56, s23
	ds_read_b128 v[198:201], v147 offset:17408
	global_load_lds_dwordx4 v130, s[26:27]
	s_mov_b32 m0, s56
	ds_read_b128 v[202:205], v147 offset:18432
	global_load_lds_dwordx4 v0, s[50:51]
	s_add_i32 m0, s56, 0x2000
	ds_read_b128 v[206:209], v147 offset:19456
	global_load_lds_dwordx4 v130, s[50:51]
	s_mov_b32 m0, s19
	ds_read_b128 v[210:213], v147 offset:20480
	global_load_lds_dwordx4 v134, s[34:35]
	s_mov_b32 m0, s31
	ds_read_b128 v[214:217], v147 offset:21504
	global_load_lds_dwordx4 v132, s[34:35]
	ds_read_b128 v[218:221], v147 offset:22528
	ds_read_b128 v[222:225], v147 offset:23552
	s_waitcnt vmcnt(8)
	s_waitcnt lgkmcnt(0)
	s_setprio 1
	s_barrier
	v_mfma_f32_16x16x32_bf16 v[62:65], v[140:143], v[194:197], v[62:65]
	v_mfma_f32_16x16x32_bf16 v[58:61], v[152:155], v[194:197], v[58:61]
	v_mfma_f32_16x16x32_bf16 v[46:49], v[140:143], v[202:205], v[46:49]
	v_mfma_f32_16x16x32_bf16 v[42:45], v[152:155], v[202:205], v[42:45]
	v_mfma_f32_16x16x32_bf16 v[30:33], v[140:143], v[210:213], v[30:33]
	v_mfma_f32_16x16x32_bf16 v[26:29], v[152:155], v[210:213], v[26:29]
	v_mfma_f32_16x16x32_bf16 v[14:17], v[140:143], v[218:221], v[14:17]
	v_mfma_f32_16x16x32_bf16 v[10:13], v[152:155], v[218:221], v[10:13]
	v_mfma_f32_16x16x32_bf16 v[62:65], v[148:151], v[198:201], v[62:65]
	v_mfma_f32_16x16x32_bf16 v[58:61], v[156:159], v[198:201], v[58:61]
	v_mfma_f32_16x16x32_bf16 v[46:49], v[148:151], v[206:209], v[46:49]
	v_mfma_f32_16x16x32_bf16 v[42:45], v[156:159], v[206:209], v[42:45]
	v_mfma_f32_16x16x32_bf16 v[30:33], v[148:151], v[214:217], v[30:33]
	v_mfma_f32_16x16x32_bf16 v[26:29], v[156:159], v[214:217], v[26:29]
	v_mfma_f32_16x16x32_bf16 v[14:17], v[148:151], v[222:225], v[14:17]
	v_mfma_f32_16x16x32_bf16 v[10:13], v[156:159], v[222:225], v[10:13]
	v_mfma_f32_16x16x32_bf16 v[54:57], v[166:169], v[194:197], v[54:57]
	v_mfma_f32_16x16x32_bf16 v[50:53], v[174:177], v[194:197], v[50:53]
	v_mfma_f32_16x16x32_bf16 v[38:41], v[166:169], v[202:205], v[38:41]
	v_mfma_f32_16x16x32_bf16 v[34:37], v[174:177], v[202:205], v[34:37]
	v_mfma_f32_16x16x32_bf16 v[22:25], v[166:169], v[210:213], v[22:25]
	v_mfma_f32_16x16x32_bf16 v[18:21], v[174:177], v[210:213], v[18:21]
	v_mfma_f32_16x16x32_bf16 v[6:9], v[166:169], v[218:221], v[6:9]
	v_mfma_f32_16x16x32_bf16 v[2:5], v[174:177], v[218:221], v[2:5]
	v_mfma_f32_16x16x32_bf16 v[54:57], v[170:173], v[198:201], v[54:57]
	v_mfma_f32_16x16x32_bf16 v[50:53], v[178:181], v[198:201], v[50:53]
	v_mfma_f32_16x16x32_bf16 v[38:41], v[170:173], v[206:209], v[38:41]
	v_mfma_f32_16x16x32_bf16 v[34:37], v[178:181], v[206:209], v[34:37]
	v_mfma_f32_16x16x32_bf16 v[22:25], v[170:173], v[214:217], v[22:25]
	v_mfma_f32_16x16x32_bf16 v[18:21], v[178:181], v[214:217], v[18:21]
	v_mfma_f32_16x16x32_bf16 v[6:9], v[170:173], v[222:225], v[6:9]
	v_mfma_f32_16x16x32_bf16 v[2:5], v[178:181], v[222:225], v[2:5]
	s_barrier
; #define PG8_STAGE(bufoff, gbase, voff) do { _Pragma("unroll") for (int _i = 0; _i < 2; ++_i) \
;         __builtin_amdgcn_global_load_lds((const unsigned*)((const char*)(gbase) + (voff)[_i]), (LAS unsigned*)(lds + (bufoff) + ldsw + _i * 8192), 16, 0, 0); } while (0)
; #define PG8_LDA(dst, b, h) do { _Pragma("unroll") for (int m = 0; m < 4; ++m) _Pragma("unroll") for (int k = 0; k < 2; ++k) dst[m][k] = *(const LAS bf16x8*)(lds + PG8_SA(b, h) + aoff + m * 2048 + k * 1024); } while (0)
; #define PG8_LDB(dst, b, h) do { _Pragma("unroll") for (int n = 0; n < 2; ++n) _Pragma("unroll") for (int k = 0; k < 2; ++k) dst[n][k] = *(const LAS bf16x8*)(lds + PG8_SB(b, h) + boff + n * 2048 + k * 1024); } while (0)
; #define PG8_MMA(ai, bj, At, Bt) do { __builtin_amdgcn_s_setprio(1); _Pragma("unroll") for (int m = 0; m < 4; ++m) _Pragma("unroll") for (int n = 0; n < 2; ++n) _Pragma("unroll") for (int k = 0; k < 2; ++k) \
;         acc[ai][bj][m][n] = __builtin_amdgcn_mfma_f32_16x16x32_bf16(Bt[n][k], At[m][k], acc[ai][bj][m][n], 0, 0, 0); __builtin_amdgcn_s_setprio(0); } while (0)
; #define PG8_WAIT_V(n) asm volatile("s_waitcnt vmcnt(" #n ")" ::: "memory")
; #define PG8_WAIT_L(n) asm volatile("s_waitcnt lgkmcnt(" #n ")" ::: "memory")
; #define PG8_BAR __builtin_amdgcn_s_barrier()
; #define PG8_SCHED __builtin_amdgcn_sched_barrier(0)
; template <class Epi>
; __device__ __forceinline__ void gemm_phase(LAS unsigned char* lds, const Gemm g, const StaticOrder& S, const Epi& E) {
;     ...
;             PG8_LDB(B0, 1, 0); PG8_LDB(B1, 1, 1); PG8_SCHED; PG8_LDA(At, 1, 0); PG8_STAGE(PG8_SA(0, 1), a2 + hstepA, voffA);
;             PG8_WAIT_V(8); PG8_WAIT_L(0); PG8_BAR; PG8_MMA(0, 0, At, B0); PG8_MMA(0, 1, At, B1); PG8_BAR; PG8_SCHED;
;             PG8_LDA(At, 1, 1); PG8_STAGE(PG8_SB(1, 0), b3, voffB); PG8_STAGE(PG8_SB(1, 1), b3 + hstepB, voffB); PG8_STAGE(PG8_SA(1, 0), a3, voffA);
;             PG8_WAIT_V(8); PG8_WAIT_L(0); PG8_BAR; PG8_MMA(1, 0, At, B0); PG8_MMA(1, 1, At, B1); PG8_BAR; PG8_SCHED;
;         }
;         if (wr == 0) PG8_BAR;
	s_setprio 0
	s_add_i32 s50, 0, 0x18000
	s_add_i32 s51, 0, 0x1c000
	v_add_u32_e32 v156, s50, v145
	v_add_u32_e32 v178, s51, v145
	ds_read_b128 v[140:143], v156
	ds_read_b128 v[148:151], v156 offset:1024
	ds_read_b128 v[152:155], v156 offset:2048
	ds_read_b128 v[156:159], v156 offset:3072
	ds_read_b128 v[166:169], v178
	ds_read_b128 v[170:173], v178 offset:1024
	ds_read_b128 v[174:177], v178 offset:2048
	ds_read_b128 v[178:181], v178 offset:3072
	s_add_u32 s34, s34, 0x80000
	s_addc_u32 s35, s35, 0
	s_mov_b32 m0, s36
	ds_read_b128 v[194:197], v147 offset:32768
	global_load_lds_dwordx4 v134, s[34:35]
	s_mov_b32 m0, s37
	ds_read_b128 v[198:201], v147 offset:33792
	global_load_lds_dwordx4 v132, s[34:35]
	ds_read_b128 v[202:205], v147 offset:34816
	ds_read_b128 v[206:209], v147 offset:35840
	ds_read_b128 v[210:213], v147 offset:36864
	ds_read_b128 v[214:217], v147 offset:37888
	ds_read_b128 v[218:221], v147 offset:38912
	ds_read_b128 v[222:225], v147 offset:39936
	s_waitcnt vmcnt(8)
	s_waitcnt lgkmcnt(0)
	s_setprio 1
	s_barrier
	v_mfma_f32_16x16x32_bf16 v[126:129], v[140:143], v[194:197], v[126:129]
	v_mfma_f32_16x16x32_bf16 v[122:125], v[152:155], v[194:197], v[122:125]
	v_mfma_f32_16x16x32_bf16 v[110:113], v[140:143], v[202:205], v[110:113]
	v_mfma_f32_16x16x32_bf16 v[106:109], v[152:155], v[202:205], v[106:109]
	v_mfma_f32_16x16x32_bf16 v[94:97], v[140:143], v[210:213], v[94:97]
	v_mfma_f32_16x16x32_bf16 v[90:93], v[152:155], v[210:213], v[90:93]
	v_mfma_f32_16x16x32_bf16 v[78:81], v[140:143], v[218:221], v[78:81]
	v_mfma_f32_16x16x32_bf16 v[74:77], v[152:155], v[218:221], v[74:77]
	v_mfma_f32_16x16x32_bf16 v[126:129], v[148:151], v[198:201], v[126:129]
	v_mfma_f32_16x16x32_bf16 v[122:125], v[156:159], v[198:201], v[122:125]
	v_mfma_f32_16x16x32_bf16 v[110:113], v[148:151], v[206:209], v[110:113]
	v_mfma_f32_16x16x32_bf16 v[106:109], v[156:159], v[206:209], v[106:109]
	v_mfma_f32_16x16x32_bf16 v[94:97], v[148:151], v[214:217], v[94:97]
	v_mfma_f32_16x16x32_bf16 v[90:93], v[156:159], v[214:217], v[90:93]
	v_mfma_f32_16x16x32_bf16 v[78:81], v[148:151], v[222:225], v[78:81]
	v_mfma_f32_16x16x32_bf16 v[74:77], v[156:159], v[222:225], v[74:77]
	v_mfma_f32_16x16x32_bf16 v[118:121], v[166:169], v[194:197], v[118:121]
	v_mfma_f32_16x16x32_bf16 v[114:117], v[174:177], v[194:197], v[114:117]
	v_mfma_f32_16x16x32_bf16 v[102:105], v[166:169], v[202:205], v[102:105]
	v_mfma_f32_16x16x32_bf16 v[98:101], v[174:177], v[202:205], v[98:101]
	v_mfma_f32_16x16x32_bf16 v[86:89], v[166:169], v[210:213], v[86:89]
	v_mfma_f32_16x16x32_bf16 v[82:85], v[174:177], v[210:213], v[82:85]
	v_mfma_f32_16x16x32_bf16 v[70:73], v[166:169], v[218:221], v[70:73]
	v_mfma_f32_16x16x32_bf16 v[66:69], v[174:177], v[218:221], v[66:69]
	v_mfma_f32_16x16x32_bf16 v[118:121], v[170:173], v[198:201], v[118:121]
	v_mfma_f32_16x16x32_bf16 v[114:117], v[178:181], v[198:201], v[114:117]
	v_mfma_f32_16x16x32_bf16 v[102:105], v[170:173], v[206:209], v[102:105]
	v_mfma_f32_16x16x32_bf16 v[98:101], v[178:181], v[206:209], v[98:101]
	v_mfma_f32_16x16x32_bf16 v[86:89], v[170:173], v[214:217], v[86:89]
	v_mfma_f32_16x16x32_bf16 v[82:85], v[178:181], v[214:217], v[82:85]
	v_mfma_f32_16x16x32_bf16 v[70:73], v[170:173], v[222:225], v[70:73]
	v_mfma_f32_16x16x32_bf16 v[66:69], v[178:181], v[222:225], v[66:69]
	s_barrier
	s_setprio 0
	s_add_i32 s32, s50, s23
	s_add_u32 s26, s26, 0x80
	s_addc_u32 s27, s27, 0
	s_mov_b32 m0, s32
	ds_read_b128 v[194:197], v147 offset:49152
	global_load_lds_dwordx4 v0, s[26:27]
	s_add_i32 m0, s32, 0x2000
	s_add_i32 s32, s51, s23
	ds_read_b128 v[198:201], v147 offset:50176
	global_load_lds_dwordx4 v130, s[26:27]
	s_add_u32 s26, s26, 0x80000
	s_addc_u32 s27, s27, 0
	s_mov_b32 m0, s32
	ds_read_b128 v[202:205], v147 offset:51200
	global_load_lds_dwordx4 v0, s[26:27]
	s_add_i32 m0, s32, 0x2000
	s_sub_u32 s34, s34, 0x7ff80
	s_subb_u32 s35, s35, 0
	ds_read_b128 v[206:209], v147 offset:52224
	global_load_lds_dwordx4 v130, s[26:27]
	s_mov_b32 m0, s38
	ds_read_b128 v[210:213], v147 offset:53248
	global_load_lds_dwordx4 v134, s[34:35]
	s_mov_b32 m0, s39
	ds_read_b128 v[214:217], v147 offset:54272
	global_load_lds_dwordx4 v132, s[34:35]
	ds_read_b128 v[218:221], v147 offset:55296
	ds_read_b128 v[222:225], v147 offset:56320
	s_waitcnt vmcnt(8)
	s_waitcnt lgkmcnt(0)
	s_setprio 1
	s_barrier
	v_mfma_f32_16x16x32_bf16 v[62:65], v[140:143], v[194:197], v[62:65]
	v_mfma_f32_16x16x32_bf16 v[58:61], v[152:155], v[194:197], v[58:61]
	v_mfma_f32_16x16x32_bf16 v[46:49], v[140:143], v[202:205], v[46:49]
	v_mfma_f32_16x16x32_bf16 v[42:45], v[152:155], v[202:205], v[42:45]
	v_mfma_f32_16x16x32_bf16 v[30:33], v[140:143], v[210:213], v[30:33]
	v_mfma_f32_16x16x32_bf16 v[26:29], v[152:155], v[210:213], v[26:29]
	v_mfma_f32_16x16x32_bf16 v[14:17], v[140:143], v[218:221], v[14:17]
	v_mfma_f32_16x16x32_bf16 v[10:13], v[152:155], v[218:221], v[10:13]
	v_mfma_f32_16x16x32_bf16 v[62:65], v[148:151], v[198:201], v[62:65]
	v_mfma_f32_16x16x32_bf16 v[58:61], v[156:159], v[198:201], v[58:61]
	v_mfma_f32_16x16x32_bf16 v[46:49], v[148:151], v[206:209], v[46:49]
	v_mfma_f32_16x16x32_bf16 v[42:45], v[156:159], v[206:209], v[42:45]
	v_mfma_f32_16x16x32_bf16 v[30:33], v[148:151], v[214:217], v[30:33]
	v_mfma_f32_16x16x32_bf16 v[26:29], v[156:159], v[214:217], v[26:29]
	v_mfma_f32_16x16x32_bf16 v[14:17], v[148:151], v[222:225], v[14:17]
	v_mfma_f32_16x16x32_bf16 v[10:13], v[156:159], v[222:225], v[10:13]
	v_mfma_f32_16x16x32_bf16 v[54:57], v[166:169], v[194:197], v[54:57]
	v_mfma_f32_16x16x32_bf16 v[50:53], v[174:177], v[194:197], v[50:53]
	v_mfma_f32_16x16x32_bf16 v[38:41], v[166:169], v[202:205], v[38:41]
	v_mfma_f32_16x16x32_bf16 v[34:37], v[174:177], v[202:205], v[34:37]
	v_mfma_f32_16x16x32_bf16 v[22:25], v[166:169], v[210:213], v[22:25]
	v_mfma_f32_16x16x32_bf16 v[18:21], v[174:177], v[210:213], v[18:21]
	v_mfma_f32_16x16x32_bf16 v[6:9], v[166:169], v[218:221], v[6:9]
	v_mfma_f32_16x16x32_bf16 v[2:5], v[174:177], v[218:221], v[2:5]
	v_mfma_f32_16x16x32_bf16 v[54:57], v[170:173], v[198:201], v[54:57]
	v_mfma_f32_16x16x32_bf16 v[50:53], v[178:181], v[198:201], v[50:53]
	v_mfma_f32_16x16x32_bf16 v[38:41], v[170:173], v[206:209], v[38:41]
	v_mfma_f32_16x16x32_bf16 v[34:37], v[178:181], v[206:209], v[34:37]
	v_mfma_f32_16x16x32_bf16 v[22:25], v[170:173], v[214:217], v[22:25]
	v_mfma_f32_16x16x32_bf16 v[18:21], v[178:181], v[214:217], v[18:21]
	v_mfma_f32_16x16x32_bf16 v[6:9], v[170:173], v[222:225], v[6:9]
	v_mfma_f32_16x16x32_bf16 v[2:5], v[178:181], v[222:225], v[2:5]
	s_barrier
	s_setprio 0
	s_add_i32 s49, s49, 2
	s_add_u32 s24, s24, 0x100
	s_addc_u32 s25, s25, 0
	s_add_u32 s47, s47, 0x100
	s_addc_u32 s48, s48, 0
	s_cmp_gt_u32 s49, 29
	s_cbranch_scc0 .LBB0_295
	s_and_b64 vcc, exec, s[8:9]
	s_cbranch_vccz .LBB0_298
	s_barrier
